# DPP/permlane swap instead of ds_bpermute also in MF, FA and attention wave reductions (on top of MA version)
# baseline (speedup 1.0000x reference)
; #define GAS __attribute__((address_space(1)))
; __device__ __forceinline__ float shx(float v, int o, int lane) { return __builtin_bit_cast(float, __builtin_amdgcn_ds_bpermute((lane ^ o) << 2, __builtin_bit_cast(int, v))); }
; __device__ __forceinline__ float wave_sum(float v, int lane) {
;     ...
;     for (int o = 1; o < 64; o <<= 1) v += shx(v, o, lane);
; __device__ __forceinline__ void phase_fa(const Params& p, Frame& F, int l, const float* xraw) {
;     ...
;                     for (int j = 0; j < 4; ++j) h[r][j] = *(const GAS f32x4*)(xraw + ((size_t)b * S + 128 * (F.wave * 8 + r4 * 4 + r) + s2) * D + 256 * j + 4 * lane);
; #pragma unroll
;                 for (int r = 0; r < 4; ++r) { const int s1 = F.wave * 8 + r4 * 4 + r; float ss = 0.f;
; #pragma unroll
;                     for (int j = 0; j < 4; ++j) ss += (h[r][j].x * h[r][j].x + h[r][j].y * h[r][j].y) + (h[r][j].z * h[r][j].z + h[r][j].w * h[r][j].w);
;                     const float rstd = rsqrtf(wave_sum(ss, lane) * (1.0f / D) + EPS);
.Lmy_fa_a:
	s_waitcnt vmcnt(0)
	v_pk_mul_f32 v[148:149], v[114:115], v[114:115]
	v_pk_mul_f32 v[150:151], v[112:113], v[112:113]
	v_pk_mul_f32 v[152:153], v[118:119], v[118:119]
	v_pk_mul_f32 v[154:155], v[116:117], v[116:117]
	v_mul_f32_e32 v156, v125, v125
	v_mul_f32_e32 v158, v127, v127
	v_pk_mov_b32 v[160:161], v[150:151], v[148:149] op_sel:[1,0]
	v_mov_b32_e32 v151, v149
	v_pk_mov_b32 v[148:149], v[154:155], v[152:153] op_sel:[1,0]
	v_mov_b32_e32 v155, v153
	v_mul_f32_e32 v162, v122, v122
	v_mul_f32_e32 v163, v123, v123
	v_pk_fma_f32 v[152:153], v[124:125], v[124:125], v[156:157] op_sel_hi:[1,1,0]
	v_pk_fma_f32 v[158:159], v[126:127], v[126:127], v[158:159] op_sel_hi:[1,1,0]
	v_pk_add_f32 v[150:151], v[160:161], v[150:151]
	v_pk_add_f32 v[148:149], v[148:149], v[154:155]
	v_mul_f32_e32 v165, v120, v120
	v_mul_f32_e32 v166, v121, v121
	v_mov_b32_e32 v153, v162
	v_mov_b32_e32 v159, v163
	v_pk_add_f32 v[150:151], v[150:151], v[150:151] op_sel:[0,1] op_sel_hi:[1,0]
	v_pk_add_f32 v[148:149], v[148:149], v[148:149] op_sel:[0,1] op_sel_hi:[1,0]
	v_pk_add_f32 v[152:153], v[152:153], v[158:159]
	v_pk_mul_f32 v[154:155], v[130:131], v[130:131]
	v_pk_mul_f32 v[158:159], v[128:129], v[128:129]
	v_pk_mul_f32 v[160:161], v[134:135], v[134:135]
	v_pk_mul_f32 v[162:163], v[132:133], v[132:133]
	v_mul_f32_e32 v156, v137, v137
	v_mul_f32_e32 v164, v139, v139
	v_mov_b32_e32 v151, v165
	v_mov_b32_e32 v149, v166
	v_mul_f32_e32 v170, v142, v142
	v_mul_f32_e32 v171, v143, v143
	v_pk_mov_b32 v[166:167], v[158:159], v[154:155] op_sel:[1,0]
	v_mov_b32_e32 v159, v155
	v_pk_mov_b32 v[154:155], v[162:163], v[160:161] op_sel:[1,0]
	v_mov_b32_e32 v163, v161
	v_pk_fma_f32 v[160:161], v[136:137], v[136:137], v[156:157] op_sel_hi:[1,1,0]
	v_pk_fma_f32 v[164:165], v[138:139], v[138:139], v[164:165] op_sel_hi:[1,1,0]
	v_pk_add_f32 v[148:149], v[150:151], v[148:149]
	v_pk_add_f32 v[150:151], v[166:167], v[158:159]
	v_pk_add_f32 v[154:155], v[154:155], v[162:163]
	v_mov_b32_e32 v161, v170
	v_mov_b32_e32 v165, v171
	v_pk_add_f32 v[148:149], v[148:149], v[152:153]
	v_mul_f32_e32 v168, v140, v140
	v_mul_f32_e32 v169, v141, v141
	v_pk_add_f32 v[150:151], v[150:151], v[150:151] op_sel:[0,1] op_sel_hi:[1,0]
	v_pk_add_f32 v[152:153], v[154:155], v[154:155] op_sel:[0,1] op_sel_hi:[1,0]
	v_pk_add_f32 v[154:155], v[160:161], v[164:165]
	v_pk_mul_f32 v[158:159], v[30:31], v[30:31]
	v_pk_mul_f32 v[160:161], v[28:29], v[28:29]
	v_pk_mul_f32 v[162:163], v[26:27], v[26:27]
	v_pk_mul_f32 v[164:165], v[24:25], v[24:25]
	v_mul_f32_e32 v156, v21, v21
	v_mul_f32_e32 v166, v23, v23
	v_mov_b32_e32 v167, v148
	v_mul_f32_e32 v185, v18, v18
	v_mul_f32_e32 v186, v19, v19
	v_mov_b32_e32 v151, v168
	v_mov_b32_e32 v153, v169
	v_pk_mov_b32 v[168:169], v[160:161], v[158:159] op_sel:[1,0]
	v_mov_b32_e32 v161, v159
	v_pk_mov_b32 v[158:159], v[164:165], v[162:163] op_sel:[1,0]
	v_mov_b32_e32 v165, v163
	v_pk_fma_f32 v[162:163], v[20:21], v[20:21], v[156:157] op_sel_hi:[1,1,0]
	v_pk_fma_f32 v[170:171], v[22:23], v[22:23], v[166:167] op_sel_hi:[1,1,0]
	v_pk_add_f32 v[150:151], v[150:151], v[152:153]
	v_pk_add_f32 v[152:153], v[168:169], v[160:161]
	v_pk_add_f32 v[158:159], v[158:159], v[164:165]
	v_mov_b32_e32 v163, v185
	v_mov_b32_e32 v171, v186
	v_mul_f32_e32 v183, v16, v16
	v_mul_f32_e32 v184, v17, v17
	v_pk_add_f32 v[150:151], v[150:151], v[154:155]
	v_pk_add_f32 v[152:153], v[152:153], v[152:153] op_sel:[0,1] op_sel_hi:[1,0]
	v_pk_add_f32 v[154:155], v[158:159], v[158:159] op_sel:[0,1] op_sel_hi:[1,0]
	v_pk_add_f32 v[158:159], v[162:163], v[170:171]
	v_pk_mul_f32 v[160:161], v[46:47], v[46:47]
	v_pk_mul_f32 v[162:163], v[44:45], v[44:45]
	v_pk_mul_f32 v[164:165], v[42:43], v[42:43]
	v_pk_mul_f32 v[168:169], v[40:41], v[40:41]
	v_mov_b32_e32 v166, v150
	v_mov_b32_e32 v148, v151
	v_mov_b32_e32 v153, v183
	v_mov_b32_e32 v155, v184
	v_pk_mov_b32 v[150:151], v[162:163], v[160:161] op_sel:[1,0]
	v_mov_b32_e32 v163, v161
	v_pk_mov_b32 v[160:161], v[168:169], v[164:165] op_sel:[1,0]
	v_mov_b32_e32 v169, v165
	v_mul_f32_e32 v156, v37, v37
	v_mul_f32_e32 v170, v39, v39
	v_pk_add_f32 v[148:149], v[166:167], v[148:149]
	v_pk_add_f32 v[152:153], v[152:153], v[154:155]
	v_pk_add_f32 v[150:151], v[150:151], v[162:163]
	v_pk_add_f32 v[154:155], v[160:161], v[168:169]
	v_mul_f32_e32 v185, v32, v32
	v_mul_f32_e32 v186, v33, v33
	v_mul_f32_e32 v187, v34, v34
	v_mul_f32_e32 v188, v35, v35
	v_pk_fma_f32 v[164:165], v[36:37], v[36:37], v[156:157] op_sel_hi:[1,1,0]
	v_pk_fma_f32 v[170:171], v[38:39], v[38:39], v[170:171] op_sel_hi:[1,1,0]
	v_mov_b32_dpp v161, v149 quad_perm:[1,0,3,2] row_mask:0xf bank_mask:0xf
	v_mov_b32_dpp v160, v148 quad_perm:[1,0,3,2] row_mask:0xf bank_mask:0xf
	v_pk_add_f32 v[150:151], v[150:151], v[150:151] op_sel:[0,1] op_sel_hi:[1,0]
	v_pk_add_f32 v[154:155], v[154:155], v[154:155] op_sel:[0,1] op_sel_hi:[1,0]
	v_mov_b32_e32 v165, v187
	v_mov_b32_e32 v171, v188
	v_mov_b32_e32 v151, v185
	v_mov_b32_e32 v155, v186
	v_pk_add_f32 v[152:153], v[152:153], v[158:159]
	v_pk_add_f32 v[158:159], v[164:165], v[170:171]
	v_pk_add_f32 v[150:151], v[150:151], v[154:155]
	v_mov_b32_e32 v163, v152
	v_pk_add_f32 v[150:151], v[150:151], v[158:159]
	s_waitcnt lgkmcnt(0)
	v_pk_add_f32 v[148:149], v[148:149], v[160:161]
	v_mov_b32_e32 v162, v150
	v_mov_b32_e32 v152, v151
	v_pk_add_f32 v[150:151], v[162:163], v[152:153]
	v_mov_b32_dpp v153, v149 quad_perm:[2,3,0,1] row_mask:0xf bank_mask:0xf
	v_mov_b32_dpp v152, v148 quad_perm:[2,3,0,1] row_mask:0xf bank_mask:0xf
	v_mov_b32_dpp v155, v151 quad_perm:[1,0,3,2] row_mask:0xf bank_mask:0xf
	v_mov_b32_dpp v154, v150 quad_perm:[1,0,3,2] row_mask:0xf bank_mask:0xf
	s_waitcnt lgkmcnt(0)
; __device__ __forceinline__ float shx(float v, int o, int lane) { return __builtin_bit_cast(float, __builtin_amdgcn_ds_bpermute((lane ^ o) << 2, __builtin_bit_cast(int, v))); }
; __device__ __forceinline__ float wave_sum(float v, int lane) {
;     ...
;     for (int o = 1; o < 64; o <<= 1) v += shx(v, o, lane);
; __device__ __forceinline__ void phase_fa(const Params& p, Frame& F, int l, const float* xraw) {
;     ...
;                 for (int r = 0; r < 4; ++r) { const int s1 = F.wave * 8 + r4 * 4 + r; float ss = 0.f;
; #pragma unroll
;                     for (int j = 0; j < 4; ++j) ss += (h[r][j].x * h[r][j].x + h[r][j].y * h[r][j].y) + (h[r][j].z * h[r][j].z + h[r][j].w * h[r][j].w);
;                     const float rstd = rsqrtf(wave_sum(ss, lane) * (1.0f / D) + EPS);
	v_pk_add_f32 v[148:149], v[148:149], v[152:153]
	s_nop 1
	v_mov_b32_dpp v153, v149 quad_perm:[3,2,1,0] row_mask:0xf bank_mask:0xf
	s_nop 1
	v_mov_b32_dpp v153, v153 row_half_mirror row_mask:0xf bank_mask:0xf
	s_waitcnt lgkmcnt(0)
	v_pk_add_f32 v[150:151], v[150:151], v[154:155]
	v_mov_b32_dpp v152, v148 quad_perm:[3,2,1,0] row_mask:0xf bank_mask:0xf
	s_nop 1
	v_mov_b32_dpp v152, v152 row_half_mirror row_mask:0xf bank_mask:0xf
	v_mov_b32_dpp v155, v151 quad_perm:[2,3,0,1] row_mask:0xf bank_mask:0xf
	v_mov_b32_dpp v154, v150 quad_perm:[2,3,0,1] row_mask:0xf bank_mask:0xf
	s_waitcnt lgkmcnt(0)
	v_pk_add_f32 v[148:149], v[148:149], v[152:153]
	s_nop 1
	v_mov_b32_dpp v153, v149 row_ror:8 row_mask:0xf bank_mask:0xf
	s_waitcnt lgkmcnt(0)
	v_pk_add_f32 v[150:151], v[150:151], v[154:155]
	v_mov_b32_dpp v152, v148 row_ror:8 row_mask:0xf bank_mask:0xf
	s_nop 0
	v_mov_b32_dpp v155, v151 quad_perm:[3,2,1,0] row_mask:0xf bank_mask:0xf
	s_nop 1
	v_mov_b32_dpp v155, v155 row_half_mirror row_mask:0xf bank_mask:0xf
	v_mov_b32_dpp v154, v150 quad_perm:[3,2,1,0] row_mask:0xf bank_mask:0xf
	s_nop 1
	v_mov_b32_dpp v154, v154 row_half_mirror row_mask:0xf bank_mask:0xf
	s_waitcnt lgkmcnt(0)
	v_pk_add_f32 v[148:149], v[148:149], v[152:153]
	v_mov_b32_e32 v153, v149
	s_nop 1
	v_permlane16_swap_b32 v153, v149
	s_waitcnt lgkmcnt(0)
	v_pk_add_f32 v[150:151], v[150:151], v[154:155]
	v_mov_b32_e32 v152, v148
	s_nop 1
	v_permlane16_swap_b32 v152, v148
	s_nop 3
	v_mov_b32_dpp v155, v151 row_ror:8 row_mask:0xf bank_mask:0xf
	v_mov_b32_dpp v154, v150 row_ror:8 row_mask:0xf bank_mask:0xf
	s_waitcnt lgkmcnt(0)
	v_pk_add_f32 v[148:149], v[148:149], v[152:153]
	v_mov_b32_e32 v153, v149
	s_nop 1
	v_permlane32_swap_b32 v153, v149
	s_waitcnt lgkmcnt(0)
	v_pk_add_f32 v[150:151], v[150:151], v[154:155]
	v_mov_b32_e32 v152, v148
	s_nop 1
	v_permlane32_swap_b32 v152, v148
	v_mov_b32_e32 v155, v151
	s_nop 1
	v_permlane16_swap_b32 v155, v151
	v_mov_b32_e32 v154, v150
	s_nop 1
	v_permlane16_swap_b32 v154, v150
	s_waitcnt lgkmcnt(0)
	v_pk_add_f32 v[148:149], v[148:149], v[152:153]
	s_nop 0
	v_pk_fma_f32 v[148:149], v[148:149], s[42:43], v[88:89] op_sel_hi:[1,0,0]
	s_waitcnt lgkmcnt(0)
	v_pk_add_f32 v[150:151], v[150:151], v[154:155]
	v_mov_b32_e32 v153, v151
	s_nop 1
	v_permlane32_swap_b32 v153, v151
	v_mov_b32_e32 v152, v150
	s_nop 1
	v_permlane32_swap_b32 v152, v150
	v_mul_f32_e32 v154, 0x4b800000, v149
	v_mul_f32_e32 v155, 0x4b800000, v148
	v_cmp_gt_f32_e64 s[2:3], s41, v148
	v_cmp_gt_f32_e64 s[4:5], s41, v149
	s_nop 0
	v_cndmask_b32_e64 v148, v148, v155, s[2:3]
	v_cndmask_b32_e64 v149, v149, v154, s[4:5]
	v_rsq_f32_e32 v154, v149
	v_rsq_f32_e32 v155, v148
	s_waitcnt lgkmcnt(0)
; #define LAS __attribute__((address_space(3)))
; __device__ __forceinline__ unsigned pk2(float lo, float hi) { const f32x2_t v = {lo, hi}; return __builtin_bit_cast(unsigned, __builtin_convertvector(v, bf16x2_t)); }
; __device__ __forceinline__ void phase_fa(const Params& p, Frame& F, int l, const float* xraw) {
;     ...
; #pragma unroll
;                     for (int j = 0; j < 4; ++j) { const f32x4 hv = h[r][j] * rstd * Av[j] + Bv[j]; const int c = 256 * j + 4 * lane;
;                         v2u o; o.x = pk2(hv.x, hv.y); o.y = pk2(hv.z, hv.w); *(LAS v2u*)(F.lds + (c >> 7) * 16384 + off_b(s1, (c & 127) >> 3) + (c & 7) * 2) = o; } } }
	v_pk_add_f32 v[148:149], v[150:151], v[152:153]
	s_nop 0
	v_pk_fma_f32 v[88:89], v[148:149], s[42:43], v[88:89] op_sel_hi:[1,0,0]
	v_mul_f32_e32 v148, 0x45800000, v154
	v_mul_f32_e32 v149, 0x45800000, v155
	v_mul_f32_e32 v151, 0x4b800000, v89
	v_mul_f32_e32 v152, 0x4b800000, v88
	v_cmp_gt_f32_e64 s[6:7], s41, v88
	v_cmp_gt_f32_e64 s[8:9], s41, v89
	v_cndmask_b32_e64 v148, v154, v148, s[4:5]
	v_cndmask_b32_e64 v150, v155, v149, s[2:3]
	v_cndmask_b32_e64 v149, v89, v151, s[8:9]
	v_cndmask_b32_e64 v151, v88, v152, s[6:7]
	v_pk_mul_f32 v[88:89], v[112:113], v[148:149] op_sel_hi:[1,0]
	v_pk_mul_f32 v[112:113], v[114:115], v[148:149] op_sel_hi:[1,0]
	v_pk_mul_f32 v[114:115], v[116:117], v[148:149] op_sel_hi:[1,0]
	v_pk_mul_f32 v[116:117], v[118:119], v[148:149] op_sel_hi:[1,0]
	v_pk_mul_f32 v[118:119], v[124:125], v[148:149] op_sel_hi:[1,0]
	v_pk_mul_f32 v[124:125], v[126:127], v[148:149] op_sel_hi:[1,0]
	v_pk_mul_f32 v[126:127], v[128:129], v[150:151] op_sel_hi:[1,0]
	v_pk_mul_f32 v[128:129], v[130:131], v[150:151] op_sel_hi:[1,0]
	v_pk_mul_f32 v[130:131], v[132:133], v[150:151] op_sel_hi:[1,0]
	v_pk_mul_f32 v[132:133], v[134:135], v[150:151] op_sel_hi:[1,0]
	v_pk_mul_f32 v[134:135], v[136:137], v[150:151] op_sel_hi:[1,0]
	v_pk_mul_f32 v[136:137], v[138:139], v[150:151] op_sel_hi:[1,0]
	v_pk_mul_f32 v[138:139], v[140:141], v[150:151] op_sel_hi:[1,0]
	v_pk_mul_f32 v[140:141], v[142:143], v[150:151] op_sel_hi:[1,0]
	v_rsq_f32_e32 v142, v149
	v_rsq_f32_e32 v143, v151
	v_pk_mul_f32 v[120:121], v[120:121], v[148:149] op_sel_hi:[1,0]
	v_pk_mul_f32 v[122:123], v[122:123], v[148:149] op_sel_hi:[1,0]
	v_pk_fma_f32 v[112:113], v[72:73], v[112:113], v[2:3]
	v_pk_fma_f32 v[88:89], v[74:75], v[88:89], v[0:1]
	v_pk_fma_f32 v[116:117], v[76:77], v[116:117], v[6:7]
	v_pk_fma_f32 v[114:115], v[78:79], v[114:115], v[4:5]
	v_pk_fma_f32 v[124:125], v[80:81], v[124:125], v[10:11]
	v_pk_fma_f32 v[118:119], v[82:83], v[118:119], v[8:9]
	v_pk_fma_f32 v[122:123], v[84:85], v[122:123], v[14:15]
	v_pk_fma_f32 v[120:121], v[86:87], v[120:121], v[12:13]
	v_pk_fma_f32 v[128:129], v[72:73], v[128:129], v[2:3]
	v_pk_fma_f32 v[126:127], v[74:75], v[126:127], v[0:1]
	v_pk_fma_f32 v[132:133], v[76:77], v[132:133], v[6:7]
	v_pk_fma_f32 v[130:131], v[78:79], v[130:131], v[4:5]
	v_pk_fma_f32 v[136:137], v[80:81], v[136:137], v[10:11]
	v_pk_fma_f32 v[134:135], v[82:83], v[134:135], v[8:9]
	v_pk_fma_f32 v[140:141], v[84:85], v[140:141], v[14:15]
	v_pk_fma_f32 v[138:139], v[86:87], v[138:139], v[12:13]
	v_cvt_pk_bf16_f32 v88, v88, v89
	v_cvt_pk_bf16_f32 v89, v112, v113
	v_cvt_pk_bf16_f32 v112, v114, v115
	v_cvt_pk_bf16_f32 v113, v116, v117
	v_cvt_pk_bf16_f32 v114, v118, v119
	v_cvt_pk_bf16_f32 v115, v124, v125
	v_cvt_pk_bf16_f32 v116, v120, v121
	v_cvt_pk_bf16_f32 v117, v122, v123
	v_cvt_pk_bf16_f32 v118, v126, v127
	v_cvt_pk_bf16_f32 v119, v128, v129
	v_cvt_pk_bf16_f32 v120, v130, v131
	v_cvt_pk_bf16_f32 v121, v132, v133
	v_cvt_pk_bf16_f32 v122, v134, v135
	v_cvt_pk_bf16_f32 v123, v136, v137
	v_cvt_pk_bf16_f32 v124, v138, v139
	v_cvt_pk_bf16_f32 v125, v140, v141
	ds_write2st64_b64 v172, v[88:89], v[112:113] offset1:64
	ds_write_b64 v173, v[114:115]
	ds_write_b64 v146, v[116:117]
	ds_write2st64_b64 v181, v[118:119], v[120:121] offset1:64
	ds_write_b64 v174, v[122:123] offset:256
	ds_write_b64 v147, v[124:125] offset:256
	v_mul_f32_e32 v88, 0x45800000, v142
	v_mul_f32_e32 v89, 0x45800000, v143
	v_cndmask_b32_e64 v88, v142, v88, s[8:9]
	v_cndmask_b32_e64 v112, v143, v89, s[6:7]
	v_pk_mul_f32 v[28:29], v[28:29], v[88:89] op_sel_hi:[1,0]
	v_pk_mul_f32 v[30:31], v[30:31], v[88:89] op_sel_hi:[1,0]
	v_pk_mul_f32 v[24:25], v[24:25], v[88:89] op_sel_hi:[1,0]
	v_pk_mul_f32 v[26:27], v[26:27], v[88:89] op_sel_hi:[1,0]
	v_pk_mul_f32 v[20:21], v[20:21], v[88:89] op_sel_hi:[1,0]
	v_pk_mul_f32 v[22:23], v[22:23], v[88:89] op_sel_hi:[1,0]
	v_pk_mul_f32 v[16:17], v[16:17], v[88:89] op_sel_hi:[1,0]
	v_pk_mul_f32 v[18:19], v[18:19], v[88:89] op_sel_hi:[1,0]
	v_pk_mul_f32 v[44:45], v[44:45], v[112:113] op_sel_hi:[1,0]
	v_pk_mul_f32 v[46:47], v[46:47], v[112:113] op_sel_hi:[1,0]
	v_pk_mul_f32 v[40:41], v[40:41], v[112:113] op_sel_hi:[1,0]
	v_pk_mul_f32 v[42:43], v[42:43], v[112:113] op_sel_hi:[1,0]
	v_pk_mul_f32 v[36:37], v[36:37], v[112:113] op_sel_hi:[1,0]
	v_pk_mul_f32 v[38:39], v[38:39], v[112:113] op_sel_hi:[1,0]
	v_pk_mul_f32 v[32:33], v[32:33], v[112:113] op_sel_hi:[1,0]
	v_pk_mul_f32 v[34:35], v[34:35], v[112:113] op_sel_hi:[1,0]
	v_pk_fma_f32 v[30:31], v[72:73], v[30:31], v[2:3]
	v_pk_fma_f32 v[28:29], v[74:75], v[28:29], v[0:1]
	v_pk_fma_f32 v[26:27], v[76:77], v[26:27], v[6:7]
	v_pk_fma_f32 v[24:25], v[78:79], v[24:25], v[4:5]
	v_pk_fma_f32 v[22:23], v[80:81], v[22:23], v[10:11]
	v_pk_fma_f32 v[20:21], v[82:83], v[20:21], v[8:9]
	v_pk_fma_f32 v[18:19], v[84:85], v[18:19], v[14:15]
	v_pk_fma_f32 v[16:17], v[86:87], v[16:17], v[12:13]
	v_pk_fma_f32 v[46:47], v[72:73], v[46:47], v[2:3]
	v_pk_fma_f32 v[44:45], v[74:75], v[44:45], v[0:1]
	v_pk_fma_f32 v[42:43], v[76:77], v[42:43], v[6:7]
	v_pk_fma_f32 v[40:41], v[78:79], v[40:41], v[4:5]
	v_pk_fma_f32 v[38:39], v[80:81], v[38:39], v[10:11]
	v_pk_fma_f32 v[36:37], v[82:83], v[36:37], v[8:9]
	v_pk_fma_f32 v[34:35], v[84:85], v[34:35], v[14:15]
	v_pk_fma_f32 v[32:33], v[86:87], v[32:33], v[12:13]
	v_cvt_pk_bf16_f32 v28, v28, v29
	v_cvt_pk_bf16_f32 v29, v30, v31
	v_cvt_pk_bf16_f32 v24, v24, v25
	v_cvt_pk_bf16_f32 v25, v26, v27
	v_cvt_pk_bf16_f32 v20, v20, v21
	v_cvt_pk_bf16_f32 v21, v22, v23
	v_cvt_pk_bf16_f32 v16, v16, v17
	v_cvt_pk_bf16_f32 v17, v18, v19
	v_cvt_pk_bf16_f32 v18, v44, v45
	v_cvt_pk_bf16_f32 v19, v46, v47
	v_cvt_pk_bf16_f32 v22, v40, v41
	v_cvt_pk_bf16_f32 v23, v42, v43
	v_cvt_pk_bf16_f32 v26, v36, v37
	v_cvt_pk_bf16_f32 v27, v38, v39
	v_cvt_pk_bf16_f32 v30, v32, v33
	v_cvt_pk_bf16_f32 v31, v34, v35
	ds_write2st64_b64 v175, v[28:29], v[24:25] offset0:1 offset1:65
	ds_write_b64 v176, v[20:21] offset:512
	ds_write_b64 v177, v[16:17] offset:512
	ds_write2st64_b64 v182, v[18:19], v[22:23] offset0:1 offset1:65
	ds_write_b64 v178, v[26:27] offset:768
	ds_write_b64 v180, v[30:31] offset:768
.Lmy_fa_b:
	s_cbranch_vccz .LBB0_231

; #define LAS __attribute__((address_space(3)))
; __device__ __forceinline__ unsigned pk2(float lo, float hi) { const f32x2_t v = {lo, hi}; return __builtin_bit_cast(unsigned, __builtin_convertvector(v, bf16x2_t)); }
; __device__ __forceinline__ float shx(float v, int o, int lane) { return __builtin_bit_cast(float, __builtin_amdgcn_ds_bpermute((lane ^ o) << 2, __builtin_bit_cast(int, v))); }
; __device__ __forceinline__ void phase_ac(const Params& p, Frame& F, int l) {
;     ...
;           for (int i = 0; i < 6; ++i) { const int row = (F.tid >> 3) + 64 * i; const v4u kq = kqa[i], vq = vqa[i];
;               float f[8] = {bf_lo(kq.x), bf_hi(kq.x), bf_lo(kq.y), bf_hi(kq.y), bf_lo(kq.z), bf_hi(kq.z), bf_lo(kq.w), bf_hi(kq.w)};
;               float ss = 0.f;
; #pragma unroll
;               for (int e = 0; e < 8; ++e) ss += f[e] * f[e];
;               ss += shx(ss, 1, F.lane); ss += shx(ss, 2, F.lane); ss += shx(ss, 4, F.lane);
;               const float r = rsqrtf(ss * (1.0f / HD) + EPS);
;               v4u ko; ko.x = pk2(f[0] * r * kg0.x, f[1] * r * kg0.y); ko.y = pk2(f[2] * r * kg0.z, f[3] * r * kg0.w); ko.z = pk2(f[4] * r * kg1.x, f[5] * r * kg1.y); ko.w = pk2(f[6] * r * kg1.z, f[7] * r * kg1.w);
;               *(LAS v4u*)(Kimg + row * AT_KP + part * 16) = ko; *(LAS v4u*)(Vimg + row * AT_VP + part * 16) = vq; } }
.Lmy_ac_a:
	s_waitcnt vmcnt(0)
	v_lshlrev_b32_e32 v66, 16, v44
	v_and_b32_e32 v67, 0xffff0000, v44
	v_lshlrev_b32_e32 v78, 16, v52
	v_and_b32_e32 v79, 0xffff0000, v52
	v_lshlrev_b32_e32 v62, 16, v45
	v_and_b32_e32 v63, 0xffff0000, v45
	v_pk_mul_f32 v[44:45], v[66:67], v[66:67]
	v_lshlrev_b32_e32 v74, 16, v53
	v_and_b32_e32 v75, 0xffff0000, v53
	v_pk_mul_f32 v[52:53], v[78:79], v[78:79]
	v_pk_mul_f32 v[64:65], v[62:63], v[62:63]
	v_pk_mul_f32 v[76:77], v[74:75], v[74:75]
	v_mov_b32_e32 v80, v52
	v_mov_b32_e32 v81, v44
	v_mov_b32_e32 v44, v53
	v_lshlrev_b32_e32 v60, 16, v46
	v_and_b32_e32 v61, 0xffff0000, v46
	v_lshlrev_b32_e32 v72, 16, v54
	v_and_b32_e32 v73, 0xffff0000, v54
	v_pk_add_f32 v[44:45], v[80:81], v[44:45]
	v_mov_b32_e32 v52, v76
	v_mov_b32_e32 v53, v64
	v_lshlrev_b32_e32 v56, 16, v47
	v_and_b32_e32 v57, 0xffff0000, v47
	v_pk_mul_f32 v[46:47], v[60:61], v[60:61]
	v_lshlrev_b32_e32 v68, 16, v55
	v_and_b32_e32 v69, 0xffff0000, v55
	v_pk_mul_f32 v[54:55], v[72:73], v[72:73]
	v_pk_add_f32 v[44:45], v[52:53], v[44:45]
	v_mov_b32_e32 v64, v77
	v_pk_add_f32 v[44:45], v[64:65], v[44:45]
	v_mov_b32_e32 v52, v54
	v_mov_b32_e32 v53, v46
	v_pk_mul_f32 v[58:59], v[56:57], v[56:57]
	v_pk_mul_f32 v[70:71], v[68:69], v[68:69]
	v_pk_add_f32 v[44:45], v[52:53], v[44:45]
	v_mov_b32_e32 v46, v55
	v_pk_add_f32 v[44:45], v[46:47], v[44:45]
	v_mov_b32_e32 v46, v70
	v_mov_b32_e32 v47, v58
	v_pk_add_f32 v[44:45], v[46:47], v[44:45]
	v_mov_b32_e32 v58, v71
	v_pk_add_f32 v[44:45], v[58:59], v[44:45]
	s_nop 1
	v_mov_b32_dpp v47, v45 quad_perm:[1,0,3,2] row_mask:0xf bank_mask:0xf
	v_mov_b32_dpp v46, v44 quad_perm:[1,0,3,2] row_mask:0xf bank_mask:0xf
	s_mov_b32 s12, 0x358637bd
	s_mov_b32 s14, 0x3c800000
	v_lshlrev_b32_e32 v70, 16, v48
	v_and_b32_e32 v71, 0xffff0000, v48
	s_waitcnt lgkmcnt(0)
	v_pk_add_f32 v[44:45], v[44:45], v[46:47]
	s_nop 1
	v_mov_b32_dpp v47, v45 quad_perm:[2,3,0,1] row_mask:0xf bank_mask:0xf
	v_mov_b32_dpp v46, v44 quad_perm:[2,3,0,1] row_mask:0xf bank_mask:0xf
	v_lshlrev_b32_e32 v64, 16, v49
	v_and_b32_e32 v65, 0xffff0000, v49
	v_pk_mul_f32 v[48:49], v[70:71], v[70:71]
	s_mov_b32 s42, 0x3c800000
	s_waitcnt lgkmcnt(0)
	v_pk_add_f32 v[44:45], v[44:45], v[46:47]
	s_nop 1
	v_mov_b32_dpp v47, v45 quad_perm:[3,2,1,0] row_mask:0xf bank_mask:0xf
	s_nop 1
	v_mov_b32_dpp v47, v47 row_half_mirror row_mask:0xf bank_mask:0xf
	v_mov_b32_dpp v46, v44 quad_perm:[3,2,1,0] row_mask:0xf bank_mask:0xf
	s_nop 1
	v_mov_b32_dpp v46, v46 row_half_mirror row_mask:0xf bank_mask:0xf
	v_mov_b32_e32 v76, v48
	s_waitcnt lgkmcnt(0)
	v_pk_add_f32 v[46:47], v[44:45], v[46:47]
	v_mov_b64_e32 v[44:45], s[12:13]
	v_pk_fma_f32 v[46:47], v[46:47], s[14:15], v[44:45] op_sel_hi:[1,0,0]
	s_mov_b32 s12, 0x800000
	v_mul_f32_e32 v52, 0x4b800000, v47
	v_cmp_gt_f32_e32 vcc, s12, v47
	s_nop 1
	v_cndmask_b32_e32 v47, v47, v52, vcc
	v_rsq_f32_e32 v47, v47
	s_nop 0
	v_mul_f32_e32 v52, 0x45800000, v47
	v_cndmask_b32_e32 v58, v47, v52, vcc
	v_pk_mul_f32 v[52:53], v[58:59], v[66:67] op_sel_hi:[0,1]
	v_pk_mul_f32 v[54:55], v[58:59], v[62:63] op_sel_hi:[0,1]
	v_pk_mul_f32 v[52:53], v[4:5], v[52:53]
	v_pk_mul_f32 v[54:55], v[6:7], v[54:55]
	v_cvt_pk_bf16_f32 v52, v52, v53
	v_cvt_pk_bf16_f32 v53, v54, v55
	v_pk_mul_f32 v[54:55], v[58:59], v[60:61] op_sel_hi:[0,1]
	v_pk_mul_f32 v[56:57], v[58:59], v[56:57] op_sel_hi:[0,1]
	v_mul_f32_e32 v47, 0x4b800000, v46
	v_cmp_gt_f32_e32 vcc, s12, v46
	v_pk_mul_f32 v[54:55], v[0:1], v[54:55]
	v_pk_mul_f32 v[56:57], v[2:3], v[56:57]
	v_cndmask_b32_e32 v46, v46, v47, vcc
	v_cvt_pk_bf16_f32 v54, v54, v55
	v_cvt_pk_bf16_f32 v55, v56, v57
	v_rsq_f32_e32 v80, v46
	v_add_u32_e32 v46, v172, v176
	v_lshlrev_b32_e32 v56, 16, v40
	v_and_b32_e32 v57, 0xffff0000, v40
	ds_write_b128 v188, v[52:55]
	ds_write_b128 v46, v[28:31] offset:55296
	v_lshlrev_b32_e32 v46, 16, v43
	v_and_b32_e32 v47, 0xffff0000, v43
	v_lshlrev_b32_e32 v52, 16, v42
	v_and_b32_e32 v53, 0xffff0000, v42
	v_lshlrev_b32_e32 v42, 16, v41
	v_and_b32_e32 v43, 0xffff0000, v41
	v_pk_mul_f32 v[40:41], v[56:57], v[56:57]
	v_pk_mul_f32 v[54:55], v[42:43], v[42:43]
	v_pk_mul_f32 v[66:67], v[64:65], v[64:65]
	v_mov_b32_e32 v77, v40
	v_mov_b32_e32 v40, v49
	v_lshlrev_b32_e32 v62, 16, v50
	v_and_b32_e32 v63, 0xffff0000, v50
	v_pk_add_f32 v[40:41], v[76:77], v[40:41]
	v_mov_b32_e32 v48, v66
	v_mov_b32_e32 v49, v54
	v_pk_mul_f32 v[30:31], v[52:53], v[52:53]
	v_lshlrev_b32_e32 v58, 16, v51
	v_and_b32_e32 v59, 0xffff0000, v51
	v_pk_mul_f32 v[50:51], v[62:63], v[62:63]
	v_pk_add_f32 v[40:41], v[48:49], v[40:41]
	v_mov_b32_e32 v54, v67
	v_pk_add_f32 v[40:41], v[54:55], v[40:41]
	v_mov_b32_e32 v48, v50
	v_mov_b32_e32 v49, v30
	v_pk_mul_f32 v[28:29], v[46:47], v[46:47]
	v_pk_mul_f32 v[60:61], v[58:59], v[58:59]
	v_pk_add_f32 v[40:41], v[48:49], v[40:41]
	v_mov_b32_e32 v30, v51
	v_pk_add_f32 v[30:31], v[30:31], v[40:41]
	v_mov_b32_e32 v40, v60
	v_mov_b32_e32 v41, v28
	v_pk_add_f32 v[30:31], v[40:41], v[30:31]
	v_mov_b32_e32 v28, v61
	v_pk_add_f32 v[30:31], v[28:29], v[30:31]
	s_nop 1
	v_mov_b32_dpp v41, v31 quad_perm:[1,0,3,2] row_mask:0xf bank_mask:0xf
	v_mov_b32_dpp v40, v30 quad_perm:[1,0,3,2] row_mask:0xf bank_mask:0xf
	v_mul_f32_e32 v81, 0x45800000, v80
	v_cndmask_b32_e32 v48, v80, v81, vcc
	v_pk_mul_f32 v[28:29], v[48:49], v[78:79] op_sel_hi:[0,1]
	v_pk_mul_f32 v[50:51], v[48:49], v[74:75] op_sel_hi:[0,1]
	s_waitcnt lgkmcnt(0)
	v_pk_add_f32 v[30:31], v[30:31], v[40:41]
	s_nop 1
	v_mov_b32_dpp v41, v31 quad_perm:[2,3,0,1] row_mask:0xf bank_mask:0xf
	v_mov_b32_dpp v40, v30 quad_perm:[2,3,0,1] row_mask:0xf bank_mask:0xf
	v_pk_mul_f32 v[28:29], v[4:5], v[28:29]
	v_pk_mul_f32 v[50:51], v[6:7], v[50:51]
	v_cvt_pk_bf16_f32 v28, v28, v29
	v_cvt_pk_bf16_f32 v29, v50, v51
	s_waitcnt lgkmcnt(0)
; #define LAS __attribute__((address_space(3)))
; __device__ __forceinline__ unsigned pk2(float lo, float hi) { const f32x2_t v = {lo, hi}; return __builtin_bit_cast(unsigned, __builtin_convertvector(v, bf16x2_t)); }
; __device__ __forceinline__ float shx(float v, int o, int lane) { return __builtin_bit_cast(float, __builtin_amdgcn_ds_bpermute((lane ^ o) << 2, __builtin_bit_cast(int, v))); }
; __device__ __forceinline__ void phase_ac(const Params& p, Frame& F, int l) {
;     ...
;           for (int i = 0; i < 6; ++i) { const int row = (F.tid >> 3) + 64 * i; const v4u kq = kqa[i], vq = vqa[i];
;               float f[8] = {bf_lo(kq.x), bf_hi(kq.x), bf_lo(kq.y), bf_hi(kq.y), bf_lo(kq.z), bf_hi(kq.z), bf_lo(kq.w), bf_hi(kq.w)};
;               float ss = 0.f;
; #pragma unroll
;               for (int e = 0; e < 8; ++e) ss += f[e] * f[e];
;               ss += shx(ss, 1, F.lane); ss += shx(ss, 2, F.lane); ss += shx(ss, 4, F.lane);
;               const float r = rsqrtf(ss * (1.0f / HD) + EPS);
;               v4u ko; ko.x = pk2(f[0] * r * kg0.x, f[1] * r * kg0.y); ko.y = pk2(f[2] * r * kg0.z, f[3] * r * kg0.w); ko.z = pk2(f[4] * r * kg1.x, f[5] * r * kg1.y); ko.w = pk2(f[6] * r * kg1.z, f[7] * r * kg1.w);
;               *(LAS v4u*)(Kimg + row * AT_KP + part * 16) = ko; *(LAS v4u*)(Vimg + row * AT_VP + part * 16) = vq; } }
	v_pk_add_f32 v[40:41], v[30:31], v[40:41]
	s_nop 1
	v_mov_b32_dpp v55, v41 quad_perm:[3,2,1,0] row_mask:0xf bank_mask:0xf
	s_nop 1
	v_mov_b32_dpp v55, v55 row_half_mirror row_mask:0xf bank_mask:0xf
	v_mov_b32_dpp v54, v40 quad_perm:[3,2,1,0] row_mask:0xf bank_mask:0xf
	s_nop 1
	v_mov_b32_dpp v54, v54 row_half_mirror row_mask:0xf bank_mask:0xf
	v_pk_mul_f32 v[50:51], v[48:49], v[72:73] op_sel_hi:[0,1]
	v_pk_mul_f32 v[30:31], v[0:1], v[50:51]
	v_pk_mul_f32 v[48:49], v[48:49], v[68:69] op_sel_hi:[0,1]
	v_cvt_pk_bf16_f32 v30, v30, v31
	s_waitcnt lgkmcnt(0)
	v_pk_add_f32 v[40:41], v[40:41], v[54:55]
	v_pk_mul_f32 v[48:49], v[2:3], v[48:49]
	v_pk_fma_f32 v[40:41], v[40:41], s[14:15], v[44:45] op_sel_hi:[1,0,0]
	s_nop 0
	v_mul_f32_e32 v31, 0x4b800000, v41
	v_cmp_gt_f32_e32 vcc, s12, v41
	s_nop 1
	v_cndmask_b32_e32 v31, v41, v31, vcc
	v_rsq_f32_e32 v41, v31
	v_cvt_pk_bf16_f32 v31, v48, v49
	ds_write_b128 v188, v[28:31] offset:9216
	ds_write_b128 v189, v[12:15] offset:55296
	v_lshlrev_b32_e32 v48, 16, v37
	v_mul_f32_e32 v12, 0x45800000, v41
	v_cndmask_b32_e32 v28, v41, v12, vcc
	v_pk_mul_f32 v[12:13], v[28:29], v[56:57] op_sel_hi:[0,1]
	v_pk_mul_f32 v[14:15], v[28:29], v[42:43] op_sel_hi:[0,1]
	v_pk_mul_f32 v[12:13], v[4:5], v[12:13]
	v_pk_mul_f32 v[14:15], v[6:7], v[14:15]
	v_cvt_pk_bf16_f32 v12, v12, v13
	v_cvt_pk_bf16_f32 v13, v14, v15
	v_pk_mul_f32 v[14:15], v[28:29], v[52:53] op_sel_hi:[0,1]
	v_pk_mul_f32 v[14:15], v[0:1], v[14:15]
	v_pk_mul_f32 v[28:29], v[28:29], v[46:47] op_sel_hi:[0,1]
	v_cvt_pk_bf16_f32 v14, v14, v15
	v_mul_f32_e32 v15, 0x4b800000, v40
	v_cmp_gt_f32_e32 vcc, s12, v40
	v_pk_mul_f32 v[28:29], v[2:3], v[28:29]
	v_lshlrev_b32_e32 v52, 16, v36
	v_cndmask_b32_e32 v15, v40, v15, vcc
	v_rsq_f32_e32 v56, v15
	v_cvt_pk_bf16_f32 v15, v28, v29
	ds_write_b128 v188, v[12:15] offset:18432
	ds_write_b128 v190, v[24:27] offset:55296
	v_lshlrev_b32_e32 v24, 16, v35
	v_and_b32_e32 v25, 0xffff0000, v35
	v_lshlrev_b32_e32 v26, 16, v34
	v_and_b32_e32 v27, 0xffff0000, v34
	v_lshlrev_b32_e32 v34, 16, v32
	v_and_b32_e32 v35, 0xffff0000, v32
	v_and_b32_e32 v53, 0xffff0000, v36
	v_lshlrev_b32_e32 v28, 16, v33
	v_and_b32_e32 v29, 0xffff0000, v33
	v_pk_mul_f32 v[32:33], v[34:35], v[34:35]
	v_and_b32_e32 v49, 0xffff0000, v37
	v_pk_mul_f32 v[36:37], v[52:53], v[52:53]
	v_pk_mul_f32 v[30:31], v[28:29], v[28:29]
	v_pk_mul_f32 v[50:51], v[48:49], v[48:49]
	v_mov_b32_e32 v54, v36
	v_mov_b32_e32 v55, v32
	v_mov_b32_e32 v32, v37
	v_lshlrev_b32_e32 v46, 16, v38
	v_and_b32_e32 v47, 0xffff0000, v38
	v_pk_add_f32 v[32:33], v[54:55], v[32:33]
	v_mov_b32_e32 v36, v50
	v_mov_b32_e32 v37, v30
	v_pk_mul_f32 v[14:15], v[26:27], v[26:27]
	v_lshlrev_b32_e32 v40, 16, v39
	v_and_b32_e32 v41, 0xffff0000, v39
	v_pk_mul_f32 v[38:39], v[46:47], v[46:47]
	v_pk_add_f32 v[32:33], v[36:37], v[32:33]
	v_mov_b32_e32 v30, v51
	v_pk_add_f32 v[30:31], v[30:31], v[32:33]
	v_mov_b32_e32 v32, v38
	v_mov_b32_e32 v33, v14
	v_pk_mul_f32 v[12:13], v[24:25], v[24:25]
	v_pk_mul_f32 v[42:43], v[40:41], v[40:41]
	v_pk_add_f32 v[30:31], v[32:33], v[30:31]
	v_mov_b32_e32 v14, v39
	v_pk_add_f32 v[14:15], v[14:15], v[30:31]
	v_mov_b32_e32 v30, v42
	v_mov_b32_e32 v31, v12
	v_pk_add_f32 v[14:15], v[30:31], v[14:15]
	v_mov_b32_e32 v12, v43
	v_pk_add_f32 v[14:15], v[12:13], v[14:15]
	s_nop 1
	v_mov_b32_dpp v31, v15 quad_perm:[1,0,3,2] row_mask:0xf bank_mask:0xf
	v_mov_b32_dpp v30, v14 quad_perm:[1,0,3,2] row_mask:0xf bank_mask:0xf
	v_mul_f32_e32 v57, 0x45800000, v56
	v_cndmask_b32_e32 v32, v56, v57, vcc
	v_pk_mul_f32 v[12:13], v[32:33], v[70:71] op_sel_hi:[0,1]
	v_pk_mul_f32 v[36:37], v[32:33], v[64:65] op_sel_hi:[0,1]
	s_waitcnt lgkmcnt(0)
; #define LAS __attribute__((address_space(3)))
; __device__ __forceinline__ unsigned pk2(float lo, float hi) { const f32x2_t v = {lo, hi}; return __builtin_bit_cast(unsigned, __builtin_convertvector(v, bf16x2_t)); }
; __device__ __forceinline__ float shx(float v, int o, int lane) { return __builtin_bit_cast(float, __builtin_amdgcn_ds_bpermute((lane ^ o) << 2, __builtin_bit_cast(int, v))); }
; __device__ __forceinline__ void phase_ac(const Params& p, Frame& F, int l) {
;     ...
;           for (int i = 0; i < 6; ++i) { const int row = (F.tid >> 3) + 64 * i; const v4u kq = kqa[i], vq = vqa[i];
;               float f[8] = {bf_lo(kq.x), bf_hi(kq.x), bf_lo(kq.y), bf_hi(kq.y), bf_lo(kq.z), bf_hi(kq.z), bf_lo(kq.w), bf_hi(kq.w)};
;               float ss = 0.f;
; #pragma unroll
;               for (int e = 0; e < 8; ++e) ss += f[e] * f[e];
;               ss += shx(ss, 1, F.lane); ss += shx(ss, 2, F.lane); ss += shx(ss, 4, F.lane);
;               const float r = rsqrtf(ss * (1.0f / HD) + EPS);
;               v4u ko; ko.x = pk2(f[0] * r * kg0.x, f[1] * r * kg0.y); ko.y = pk2(f[2] * r * kg0.z, f[3] * r * kg0.w); ko.z = pk2(f[4] * r * kg1.x, f[5] * r * kg1.y); ko.w = pk2(f[6] * r * kg1.z, f[7] * r * kg1.w);
;               *(LAS v4u*)(Kimg + row * AT_KP + part * 16) = ko; *(LAS v4u*)(Vimg + row * AT_VP + part * 16) = vq; } }
;         for (int i = F.tid; i < 4 * 257; i += NTHR) { const int gg = i / 257, r = i - gg * 257; btab[gg * 260 + r] = biasrel[(kvh * 4 + gg) * 257 + r] - ATT_COFF; }
	v_pk_add_f32 v[14:15], v[14:15], v[30:31]
	s_nop 1
	v_mov_b32_dpp v31, v15 quad_perm:[2,3,0,1] row_mask:0xf bank_mask:0xf
	v_mov_b32_dpp v30, v14 quad_perm:[2,3,0,1] row_mask:0xf bank_mask:0xf
	v_pk_mul_f32 v[12:13], v[4:5], v[12:13]
	v_pk_mul_f32 v[36:37], v[6:7], v[36:37]
	v_cvt_pk_bf16_f32 v12, v12, v13
	v_cvt_pk_bf16_f32 v13, v36, v37
	s_waitcnt lgkmcnt(0)
	v_pk_add_f32 v[30:31], v[14:15], v[30:31]
	s_nop 1
	v_mov_b32_dpp v39, v31 quad_perm:[3,2,1,0] row_mask:0xf bank_mask:0xf
	s_nop 1
	v_mov_b32_dpp v39, v39 row_half_mirror row_mask:0xf bank_mask:0xf
	v_mov_b32_dpp v38, v30 quad_perm:[3,2,1,0] row_mask:0xf bank_mask:0xf
	s_nop 1
	v_mov_b32_dpp v38, v38 row_half_mirror row_mask:0xf bank_mask:0xf
	v_pk_mul_f32 v[36:37], v[32:33], v[62:63] op_sel_hi:[0,1]
	v_pk_mul_f32 v[14:15], v[0:1], v[36:37]
	v_pk_mul_f32 v[32:33], v[32:33], v[58:59] op_sel_hi:[0,1]
	v_cvt_pk_bf16_f32 v14, v14, v15
	s_waitcnt lgkmcnt(0)
	v_pk_add_f32 v[30:31], v[30:31], v[38:39]
	v_pk_mul_f32 v[32:33], v[2:3], v[32:33]
	v_pk_fma_f32 v[30:31], v[30:31], s[14:15], v[44:45] op_sel_hi:[1,0,0]
	s_nop 0
	v_mul_f32_e32 v15, 0x4b800000, v31
	v_cmp_gt_f32_e32 vcc, s12, v31
	s_nop 1
	v_cndmask_b32_e32 v15, v31, v15, vcc
	v_rsq_f32_e32 v31, v15
	v_cvt_pk_bf16_f32 v15, v32, v33
	ds_write_b128 v188, v[12:15] offset:27648
	ds_write_b128 v191, v[8:11] offset:55296
	v_mul_f32_e32 v8, 0x45800000, v31
	v_cndmask_b32_e32 v12, v31, v8, vcc
	v_pk_mul_f32 v[8:9], v[12:13], v[34:35] op_sel_hi:[0,1]
	v_pk_mul_f32 v[10:11], v[12:13], v[28:29] op_sel_hi:[0,1]
	v_pk_mul_f32 v[8:9], v[4:5], v[8:9]
	v_pk_mul_f32 v[10:11], v[6:7], v[10:11]
	v_cvt_pk_bf16_f32 v8, v8, v9
	v_cvt_pk_bf16_f32 v9, v10, v11
	v_pk_mul_f32 v[10:11], v[12:13], v[26:27] op_sel_hi:[0,1]
	v_pk_mul_f32 v[10:11], v[0:1], v[10:11]
	v_cmp_gt_f32_e32 vcc, s12, v30
	v_cvt_pk_bf16_f32 v10, v10, v11
	v_mul_f32_e32 v11, 0x4b800000, v30
	v_cndmask_b32_e32 v11, v30, v11, vcc
	v_rsq_f32_e32 v14, v11
	v_pk_mul_f32 v[12:13], v[12:13], v[24:25] op_sel_hi:[0,1]
	v_pk_mul_f32 v[12:13], v[2:3], v[12:13]
	s_nop 0
	v_cvt_pk_bf16_f32 v11, v12, v13
	ds_write_b128 v188, v[8:11] offset:36864
	ds_write_b128 v192, v[20:23] offset:55296
	v_mul_f32_e32 v8, 0x45800000, v14
	v_cndmask_b32_e32 v8, v14, v8, vcc
	v_pk_mul_f32 v[10:11], v[8:9], v[52:53] op_sel_hi:[0,1]
	v_pk_mul_f32 v[4:5], v[4:5], v[10:11]
	v_pk_mul_f32 v[10:11], v[8:9], v[48:49] op_sel_hi:[0,1]
	v_pk_mul_f32 v[6:7], v[6:7], v[10:11]
	v_cvt_pk_bf16_f32 v4, v4, v5
	v_cvt_pk_bf16_f32 v5, v6, v7
	v_pk_mul_f32 v[6:7], v[8:9], v[46:47] op_sel_hi:[0,1]
	v_pk_mul_f32 v[0:1], v[0:1], v[6:7]
	s_nop 0
	v_cvt_pk_bf16_f32 v6, v0, v1
	v_pk_mul_f32 v[0:1], v[8:9], v[40:41] op_sel_hi:[0,1]
	v_pk_mul_f32 v[0:1], v[2:3], v[0:1]
	s_nop 0
	v_cvt_pk_bf16_f32 v7, v0, v1
	ds_write_b128 v188, v[4:7] offset:46080
	ds_write_b128 v193, v[16:19] offset:55296
	v_readlane_b32 s28, v254, 19
	v_add_u32_e32 v0, 0xffffff80, v147
	v_cmp_gt_u32_e32 vcc, 0x101, v0
	v_min_u32_e32 v0, 0x100, v0
	s_mul_i32 s27, s24, 0x404
	v_add_u32_e32 v0, s27, v0
	v_mov_b32_e32 v1, 0
	v_lshl_add_u64 v[0:1], v[0:1], 2, s[6:7]
	global_load_dword v4, v[0:1], off
	global_load_dword v5, v[0:1], off offset:1028
	global_load_dword v6, v[0:1], off offset:2056
	global_load_dword v7, v[0:1], off offset:3084
	v_lshl_add_u32 v2, v147, 2, s28
	v_mov_b32_e32 v3, 0xf149f2ca
	s_waitcnt vmcnt(0)
	v_add_f32_e32 v4, 0xc1800000, v4
	v_add_f32_e32 v5, 0xc1800000, v5
	v_add_f32_e32 v6, 0xc1800000, v6
	v_add_f32_e32 v7, 0xc1800000, v7
	v_cndmask_b32_e32 v4, v3, v4, vcc
	v_cndmask_b32_e32 v5, v3, v5, vcc
	v_cndmask_b32_e32 v6, v3, v6, vcc
	v_cndmask_b32_e32 v7, v3, v7, vcc
	ds_write_b32 v2, v4
	ds_write_b32 v2, v5 offset:2048
	ds_write_b32 v2, v6 offset:4096
	ds_write_b32 v2, v7 offset:6144

; #define GAS __attribute__((address_space(1)))
; __device__ __forceinline__ float shx(float v, int o, int lane) { return __builtin_bit_cast(float, __builtin_amdgcn_ds_bpermute((lane ^ o) << 2, __builtin_bit_cast(int, v))); }
; __device__ __forceinline__ void phase_ac(const Params& p, Frame& F, int l) {
;     ...
;             for (int q2 = 0; q2 < 2; ++q2) { const int tok = n * 128 + th * 64 + 32 * qh + 16 * q2 + ql; const bf16* qp = QKV + ((size_t)b * S + tok) * QKVN + h * HD + 8 * g4;
;                 const v4u w0 = *(const GAS v4u*)qp, w1 = *(const GAS v4u*)(qp + 32);
;                 float f[16] = {bf_lo(w0.x), bf_hi(w0.x), bf_lo(w0.y), bf_hi(w0.y), bf_lo(w0.z), bf_hi(w0.z), bf_lo(w0.w), bf_hi(w0.w), bf_lo(w1.x), bf_hi(w1.x), bf_lo(w1.y), bf_hi(w1.y), bf_lo(w1.z), bf_hi(w1.z), bf_lo(w1.w), bf_hi(w1.w)};
;                 float ss = 0.f;
; #pragma unroll
;                 for (int e = 0; e < 16; ++e) ss += f[e] * f[e];
;                 ss += shx(ss, 16, F.lane); ss += shx(ss, 32, F.lane);
.LBB0_336:
	v_or_b32_e32 v144, s14, v194
	v_lshl_add_u64 v[16:17], s[8:9], 0, v[144:145]
	s_movk_i32 s15, 0xc00
	s_xor_b64 s[12:13], s[2:3], -1
	v_mad_u64_u32 v[18:19], s[2:3], v16, s15, v[164:165]
	v_mad_i32_i24 v19, v17, s15, v19
	global_load_dwordx4 v[34:37], v[18:19], off
	s_nop 0
	global_load_dwordx4 v[16:19], v[18:19], off offset:64
	v_or_b32_e32 v168, 16, v144
	v_mov_b32_e32 v169, v145
	v_lshl_add_u64 v[42:43], s[8:9], 0, v[168:169]
	v_mad_u64_u32 v[58:59], s[2:3], v42, s15, v[164:165]
	v_mad_i32_i24 v59, v43, s15, v59
	global_load_dwordx4 v[42:45], v[58:59], off offset:64
	s_nop 0
	global_load_dwordx4 v[58:61], v[58:59], off
	v_mov_b32_e32 v199, v184
	v_mov_b32_e32 v200, v180
	s_mov_b32 s34, 0
	s_waitcnt vmcnt(3)
	v_lshlrev_b32_e32 v30, 16, v35
	s_waitcnt vmcnt(2)
	v_lshlrev_b32_e32 v26, 16, v17
	v_and_b32_e32 v27, 0xffff0000, v17
	v_lshlrev_b32_e32 v20, 16, v16
	v_and_b32_e32 v21, 0xffff0000, v16
	v_and_b32_e32 v31, 0xffff0000, v35
	v_lshlrev_b32_e32 v16, 16, v34
	v_and_b32_e32 v17, 0xffff0000, v34
	v_lshlrev_b32_e32 v24, 16, v19
	v_and_b32_e32 v25, 0xffff0000, v19
	v_lshlrev_b32_e32 v22, 16, v18
	v_and_b32_e32 v23, 0xffff0000, v18
	v_lshlrev_b32_e32 v28, 16, v37
	v_and_b32_e32 v29, 0xffff0000, v37
	v_lshlrev_b32_e32 v18, 16, v36
	v_and_b32_e32 v19, 0xffff0000, v36
	v_mov_b32_e32 v79, v17
	v_mov_b32_e32 v77, v16
	v_mov_b32_e32 v73, v30
	v_mov_b32_e32 v75, v31
	v_mov_b32_e32 v69, v18
	v_mov_b32_e32 v71, v19
	v_pk_mul_f32 v[54:55], v[20:21], v[20:21]
	v_pk_mul_f32 v[52:53], v[26:27], v[26:27]
	v_pk_mul_f32 v[50:51], v[22:23], v[22:23]
	v_pk_mul_f32 v[32:33], v[24:25], v[24:25]
	s_mov_b32 s2, 0x800000
	s_waitcnt vmcnt(0)
	v_and_b32_e32 v49, 0xffff0000, v58
	v_lshlrev_b32_e32 v48, 16, v58
	v_mov_b32_e32 v78, v49
	v_lshlrev_b32_e32 v46, 16, v59
	v_mov_b32_e32 v76, v48
	v_pk_mul_f32 v[78:79], v[78:79], v[78:79]
	v_and_b32_e32 v47, 0xffff0000, v59
	v_mov_b32_e32 v72, v46
	v_pk_fma_f32 v[76:77], v[76:77], v[76:77], v[78:79]
	s_waitcnt vmcnt(0)
	v_lshlrev_b32_e32 v36, 16, v44
	v_and_b32_e32 v37, 0xffff0000, v44
	v_lshlrev_b32_e32 v44, 16, v60
	v_mov_b32_e32 v74, v47
	v_pk_fma_f32 v[72:73], v[72:73], v[72:73], v[76:77]
	v_lshlrev_b32_e32 v34, 16, v45
	v_and_b32_e32 v35, 0xffff0000, v45
	v_and_b32_e32 v45, 0xffff0000, v60
	v_mov_b32_e32 v68, v44
	v_pk_fma_f32 v[72:73], v[74:75], v[74:75], v[72:73]
	v_lshlrev_b32_e32 v40, 16, v42
	v_and_b32_e32 v41, 0xffff0000, v42
	v_lshlrev_b32_e32 v42, 16, v61
	v_mov_b32_e32 v70, v45
	v_pk_fma_f32 v[68:69], v[68:69], v[68:69], v[72:73]
	v_lshlrev_b32_e32 v38, 16, v43
	v_and_b32_e32 v39, 0xffff0000, v43
	v_and_b32_e32 v43, 0xffff0000, v61
	v_mov_b32_e32 v58, v42
	v_mov_b32_e32 v59, v28
	v_pk_fma_f32 v[68:69], v[70:71], v[70:71], v[68:69]
	v_pk_mul_f32 v[66:67], v[40:41], v[40:41]
	v_mov_b32_e32 v60, v43
	v_mov_b32_e32 v61, v29
	v_pk_fma_f32 v[58:59], v[58:59], v[58:59], v[68:69]
	v_pk_mul_f32 v[64:65], v[38:39], v[38:39]
	v_pk_fma_f32 v[58:59], v[60:61], v[60:61], v[58:59]
	v_mov_b32_e32 v60, v66
	v_mov_b32_e32 v61, v54
	v_pk_add_f32 v[58:59], v[60:61], v[58:59]
	v_mov_b32_e32 v54, v67
	v_pk_add_f32 v[54:55], v[54:55], v[58:59]
	v_mov_b32_e32 v58, v64
	v_mov_b32_e32 v59, v52
	v_pk_mul_f32 v[62:63], v[36:37], v[36:37]
	v_pk_add_f32 v[54:55], v[58:59], v[54:55]
	v_mov_b32_e32 v52, v65
	v_pk_add_f32 v[52:53], v[52:53], v[54:55]
	v_mov_b32_e32 v54, v62
	v_mov_b32_e32 v55, v50
	v_pk_mul_f32 v[56:57], v[34:35], v[34:35]
	v_pk_add_f32 v[52:53], v[54:55], v[52:53]
	v_mov_b32_e32 v50, v63
	v_pk_add_f32 v[50:51], v[50:51], v[52:53]
	v_mov_b32_e32 v52, v56
	v_mov_b32_e32 v53, v32
	v_pk_add_f32 v[50:51], v[52:53], v[50:51]
	v_mov_b32_e32 v32, v57
	v_pk_add_f32 v[32:33], v[32:33], v[50:51]
	v_mov_b32_e32 v51, v33
	s_nop 1
	v_permlane16_swap_b32 v51, v33
	v_mov_b32_e32 v50, v32
	s_nop 1
	v_permlane16_swap_b32 v50, v32
	v_mov_b32_e32 v52, 0
	v_mov_b32_e32 v53, v52
	v_mov_b32_e32 v54, v52
	v_mov_b32_e32 v55, v52
	s_waitcnt lgkmcnt(0)
; __device__ __forceinline__ unsigned pk2(float lo, float hi) { const f32x2_t v = {lo, hi}; return __builtin_bit_cast(unsigned, __builtin_convertvector(v, bf16x2_t)); }
; __device__ __forceinline__ float shx(float v, int o, int lane) { return __builtin_bit_cast(float, __builtin_amdgcn_ds_bpermute((lane ^ o) << 2, __builtin_bit_cast(int, v))); }
; __device__ __forceinline__ void phase_ac(const Params& p, Frame& F, int l) {
;     ...
;                 ss += shx(ss, 16, F.lane); ss += shx(ss, 32, F.lane);
;                 const float r = rsqrtf(ss * (1.0f / HD) + EPS) * (0.125f * LOG2E);
; #pragma unroll
;                 for (int ds = 0; ds < 2; ++ds) { v4u o; o.x = pk2(f[8 * ds + 0] * r * qa[ds][0].x, f[8 * ds + 1] * r * qa[ds][0].y); o.y = pk2(f[8 * ds + 2] * r * qa[ds][0].z, f[8 * ds + 3] * r * qa[ds][0].w);
;                     o.z = pk2(f[8 * ds + 4] * r * qa[ds][1].x, f[8 * ds + 5] * r * qa[ds][1].y); o.w = pk2(f[8 * ds + 6] * r * qa[ds][1].z, f[8 * ds + 7] * r * qa[ds][1].w);
;                     qf[q2][ds] = __builtin_bit_cast(bf16x8, o); } }
;             f32x4 osum[2]; f32x4 oacc[4][2];
; #pragma unroll
;             for (int q2 = 0; q2 < 2; ++q2) { osum[q2] = (f32x4){0.f, 0.f, 0.f, 0.f};
; #pragma unroll
;                 for (int db = 0; db < 4; ++db) oacc[db][q2] = (f32x4){0.f, 0.f, 0.f, 0.f}; }
	v_pk_add_f32 v[32:33], v[32:33], v[50:51]
	v_mov_b32_e32 v51, v33
	s_nop 1
	v_permlane32_swap_b32 v51, v33
	v_mov_b32_e32 v50, v32
	s_nop 1
	v_permlane32_swap_b32 v50, v32
	v_mov_b32_e32 v64, v52
	v_mov_b32_e32 v65, v52
	v_mov_b32_e32 v66, v52
	v_mov_b32_e32 v67, v52
	s_waitcnt lgkmcnt(0)
	v_pk_add_f32 v[32:33], v[32:33], v[50:51]
	v_mov_b32_e32 v56, v52
	v_pk_fma_f32 v[32:33], v[32:33], s[42:43], v[240:241] op_sel_hi:[1,0,0]
	v_mov_b32_e32 v57, v52
	v_mul_f32_e32 v50, 0x4b800000, v33
	v_cmp_gt_f32_e32 vcc, s2, v32
	v_cmp_gt_f32_e64 s[2:3], s2, v33
	v_mov_b32_e32 v58, v52
	v_mov_b32_e32 v59, v52
	v_cndmask_b32_e64 v33, v33, v50, s[2:3]
	v_rsq_f32_e32 v33, v33
	v_mov_b32_e32 v68, v52
	v_mov_b32_e32 v69, v52
	v_mov_b32_e32 v70, v52
	v_mul_f32_e32 v50, 0x45800000, v33
	v_cndmask_b32_e64 v33, v33, v50, s[2:3]
	v_mul_f32_e32 v50, 0x3e38aa3b, v33
	v_pk_mul_f32 v[22:23], v[50:51], v[22:23] op_sel_hi:[0,1]
	v_pk_mul_f32 v[24:25], v[50:51], v[24:25] op_sel_hi:[0,1]
	v_pk_mul_f32 v[22:23], v[12:13], v[22:23]
	v_pk_mul_f32 v[24:25], v[14:15], v[24:25]
	v_cvt_pk_bf16_f32 v22, v22, v23
	v_cvt_pk_bf16_f32 v23, v24, v25
	v_mul_f32_e32 v24, 0x4b800000, v32
	v_cndmask_b32_e32 v24, v32, v24, vcc
	v_rsq_f32_e32 v24, v24
	v_pk_mul_f32 v[20:21], v[50:51], v[20:21] op_sel_hi:[0,1]
	v_pk_mul_f32 v[26:27], v[50:51], v[26:27] op_sel_hi:[0,1]
	v_pk_mul_f32 v[20:21], v[8:9], v[20:21]
	v_mul_f32_e32 v25, 0x45800000, v24
	v_cndmask_b32_e32 v24, v24, v25, vcc
	v_pk_mul_f32 v[26:27], v[10:11], v[26:27]
	v_mul_f32_e32 v32, 0x3e38aa3b, v24
	v_pk_mul_f32 v[18:19], v[50:51], v[18:19] op_sel_hi:[0,1]
	v_pk_mul_f32 v[28:29], v[50:51], v[28:29] op_sel_hi:[0,1]
	v_cvt_pk_bf16_f32 v20, v20, v21
	v_cvt_pk_bf16_f32 v21, v26, v27
	v_pk_mul_f32 v[24:25], v[32:33], v[48:49] op_sel_hi:[0,1]
	v_pk_mul_f32 v[26:27], v[32:33], v[46:47] op_sel_hi:[0,1]
	v_pk_mul_f32 v[18:19], v[4:5], v[18:19]
	v_pk_mul_f32 v[28:29], v[6:7], v[28:29]
	v_pk_mul_f32 v[24:25], v[0:1], v[24:25]
	v_pk_mul_f32 v[26:27], v[2:3], v[26:27]
	v_pk_mul_f32 v[16:17], v[50:51], v[16:17] op_sel_hi:[0,1]
	v_pk_mul_f32 v[30:31], v[50:51], v[30:31] op_sel_hi:[0,1]
	v_cvt_pk_bf16_f32 v18, v18, v19
	v_cvt_pk_bf16_f32 v19, v28, v29
	v_cvt_pk_bf16_f32 v24, v24, v25
	v_cvt_pk_bf16_f32 v25, v26, v27
	v_pk_mul_f32 v[26:27], v[32:33], v[44:45] op_sel_hi:[0,1]
	v_pk_mul_f32 v[28:29], v[32:33], v[42:43] op_sel_hi:[0,1]
	v_pk_mul_f32 v[16:17], v[0:1], v[16:17]
	v_pk_mul_f32 v[30:31], v[2:3], v[30:31]
	v_pk_mul_f32 v[26:27], v[4:5], v[26:27]
	v_pk_mul_f32 v[28:29], v[6:7], v[28:29]
	v_cvt_pk_bf16_f32 v16, v16, v17
	v_cvt_pk_bf16_f32 v17, v30, v31
	v_cvt_pk_bf16_f32 v26, v26, v27
	v_cvt_pk_bf16_f32 v27, v28, v29
	v_pk_mul_f32 v[28:29], v[32:33], v[40:41] op_sel_hi:[0,1]
	v_pk_mul_f32 v[30:31], v[32:33], v[38:39] op_sel_hi:[0,1]
	v_pk_mul_f32 v[28:29], v[8:9], v[28:29]
	v_pk_mul_f32 v[30:31], v[10:11], v[30:31]
	v_cvt_pk_bf16_f32 v28, v28, v29
	v_cvt_pk_bf16_f32 v29, v30, v31
	v_pk_mul_f32 v[30:31], v[32:33], v[36:37] op_sel_hi:[0,1]
	v_pk_mul_f32 v[32:33], v[32:33], v[34:35] op_sel_hi:[0,1]
	v_pk_mul_f32 v[30:31], v[12:13], v[30:31]
	v_pk_mul_f32 v[32:33], v[14:15], v[32:33]
	v_cvt_pk_bf16_f32 v30, v30, v31
	v_cvt_pk_bf16_f32 v31, v32, v33
	v_add_u32_e32 v32, s14, v156
	s_or_b32 s2, s14, s22
	v_lshlrev_b32_e32 v33, 2, v32
	s_or_b32 s25, s2, 0x80
	s_or_b32 s27, s2, 0x90
	s_or_b32 s28, s2, 15
	s_or_b32 s29, s2, 31
	v_sub_u32_e32 v197, v186, v33
	v_sub_u32_e32 v198, v140, v32
	v_mov_b32_e32 v44, v52
	v_mov_b32_e32 v45, v52
	v_mov_b32_e32 v46, v52
	v_mov_b32_e32 v47, v52
	v_mov_b32_e32 v36, v52
	v_mov_b32_e32 v37, v52
	v_mov_b32_e32 v38, v52
	v_mov_b32_e32 v39, v52
	v_mov_b32_e32 v48, v52
	v_mov_b32_e32 v49, v52
	v_mov_b32_e32 v50, v52
	v_mov_b32_e32 v51, v52
	v_mov_b32_e32 v32, v52
	v_mov_b32_e32 v33, v52
	v_mov_b32_e32 v34, v52
	v_mov_b32_e32 v35, v52
	v_mov_b32_e32 v40, v52
	v_mov_b32_e32 v41, v52
	v_mov_b32_e32 v42, v52
	v_mov_b32_e32 v43, v52
	v_mov_b32_e32 v71, v52
	v_mov_b32_e32 v60, v52
	v_mov_b32_e32 v61, v52
	v_mov_b32_e32 v62, v52
	v_mov_b32_e32 v63, v52
.Lmy_ac_c:
	s_branch .LBB0_339

; #define GAS __attribute__((address_space(1)))
; __device__ __forceinline__ unsigned pk2(float lo, float hi) { const f32x2_t v = {lo, hi}; return __builtin_bit_cast(unsigned, __builtin_convertvector(v, bf16x2_t)); }
; __device__ __forceinline__ float shx(float v, int o, int lane) { return __builtin_bit_cast(float, __builtin_amdgcn_ds_bpermute((lane ^ o) << 2, __builtin_bit_cast(int, v))); }
; __device__ __forceinline__ float wave_sum(float v, int lane) {
;     ...
;     for (int o = 1; o < 64; o <<= 1) v += shx(v, o, lane);
; __device__ __forceinline__ void phase_mf(const Params& p, Frame& F, int l, const bool dry) {
;     ...
;             ss += (x0.x * x0.x + x0.y * x0.y) + (x0.z * x0.z + x0.w * x0.w) + (x1.x * x1.x + x1.y * x1.y) + (x1.z * x1.z + x1.w * x1.w); }
;         if (nxt) { const float rstd = rsqrtf(wave_sum(ss, F.lane) * (1.0f / D) + EPS);
; #pragma unroll
;             for (int j = 0; j < 2; ++j) { const int c0 = 512 * j + 8 * F.lane; v4u o; float hv[8];
; #pragma unroll
;                 for (int i = 0; i < 8; ++i) hv[i] = acc[8 * j + i] * rstd * Anv[j][i >> 2][i & 3] + Bnv[j][i >> 2][i & 3];
;                 o.x = pk2(hv[0], hv[1]); o.y = pk2(hv[2], hv[3]); o.z = pk2(hv[4], hv[5]); o.w = pk2(hv[6], hv[7]); *(GAS v4u*)(H + (size_t)row * D + c0) = o; } }
.LBB0_1456:
	v_mul_f32_e32 v48, v37, v37
	v_mul_f32_e32 v49, v39, v39
	v_fmac_f32_e32 v48, v36, v36
	v_fmac_f32_e32 v49, v38, v38
	v_add_f32_e32 v48, v48, v49
	v_mul_f32_e32 v49, v41, v41
	v_fmac_f32_e32 v49, v40, v40
	v_add_f32_e32 v48, v48, v49
	v_mul_f32_e32 v49, v43, v43
	v_fmac_f32_e32 v49, v42, v42
	v_add_f32_e32 v84, v49, v48
	v_pk_mul_f32 v[48:49], v[34:35], v[34:35]
	v_pk_mul_f32 v[50:51], v[32:33], v[32:33]
	s_mov_b32 s5, 0x800000
	v_pk_mov_b32 v[52:53], v[50:51], v[48:49] op_sel:[1,0]
	v_mov_b32_e32 v51, v49
	v_pk_add_f32 v[48:49], v[52:53], v[50:51]
	v_pk_mul_f32 v[50:51], v[46:47], v[46:47]
	v_pk_mul_f32 v[52:53], v[44:45], v[44:45]
	v_mov_b32_e32 v54, v50
	v_mov_b32_e32 v55, v52
	v_mov_b32_e32 v52, v51
	v_pk_add_f32 v[50:51], v[54:55], v[52:53]
	v_add_f32_e32 v48, v48, v49
	v_add_f32_e32 v48, v48, v51
	v_add_f32_e32 v48, v50, v48
	v_add_f32_e32 v48, v84, v48
	s_nop 1
	v_mov_b32_dpp v49, v48 quad_perm:[1,0,3,2] row_mask:0xf bank_mask:0xf
	s_waitcnt lgkmcnt(0)
	v_add_f32_e32 v48, v48, v49
	s_nop 1
	v_mov_b32_dpp v49, v48 quad_perm:[2,3,0,1] row_mask:0xf bank_mask:0xf
	s_waitcnt lgkmcnt(0)
	v_add_f32_e32 v48, v48, v49
	s_nop 1
	v_mov_b32_dpp v49, v48 quad_perm:[3,2,1,0] row_mask:0xf bank_mask:0xf
	s_nop 1
	v_mov_b32_dpp v49, v49 row_half_mirror row_mask:0xf bank_mask:0xf
	s_waitcnt lgkmcnt(0)
	v_add_f32_e32 v48, v48, v49
	s_nop 1
	v_mov_b32_dpp v49, v48 row_ror:8 row_mask:0xf bank_mask:0xf
	s_waitcnt lgkmcnt(0)
	v_add_f32_e32 v48, v48, v49
	v_mov_b32_e32 v49, v48
	s_nop 1
	v_permlane16_swap_b32 v49, v48
	s_waitcnt lgkmcnt(0)
	v_add_f32_e32 v48, v48, v49
	v_mov_b32_e32 v49, v48
	s_nop 1
	v_permlane32_swap_b32 v49, v48
	s_waitcnt lgkmcnt(0)
	v_add_f32_e32 v48, v48, v49
	v_fmamk_f32 v48, v48, 0x3a800000, v240
	v_mul_f32_e32 v49, 0x4b800000, v48
	v_cmp_gt_f32_e32 vcc, s5, v48
	s_nop 1
	v_cndmask_b32_e32 v48, v48, v49, vcc
	v_rsq_f32_e32 v48, v48
	s_nop 0
	v_mul_f32_e32 v49, 0x45800000, v48
	v_cndmask_b32_e32 v48, v48, v49, vcc
	v_pk_mul_f32 v[36:37], v[36:37], v[48:49] op_sel_hi:[1,0]
	v_pk_mul_f32 v[38:39], v[38:39], v[48:49] op_sel_hi:[1,0]
	v_pk_mul_f32 v[40:41], v[40:41], v[48:49] op_sel_hi:[1,0]
	v_pk_mul_f32 v[42:43], v[42:43], v[48:49] op_sel_hi:[1,0]
	v_pk_fma_f32 v[36:37], v[62:63], v[36:37], v[8:9]
	v_pk_fma_f32 v[38:39], v[64:65], v[38:39], v[10:11]
	v_pk_fma_f32 v[40:41], v[60:61], v[40:41], v[12:13]
	v_pk_fma_f32 v[42:43], v[66:67], v[42:43], v[14:15]
	v_cvt_pk_bf16_f32 v36, v36, v37
	v_cvt_pk_bf16_f32 v37, v38, v39
	v_cvt_pk_bf16_f32 v38, v40, v41
	v_cvt_pk_bf16_f32 v39, v42, v43
	v_lshl_add_u64 v[40:41], v[80:81], 0, s[8:9]
	global_store_dwordx4 v[40:41], v[36:39], off
	v_pk_mul_f32 v[32:33], v[32:33], v[48:49] op_sel_hi:[1,0]
	v_pk_mul_f32 v[34:35], v[34:35], v[48:49] op_sel_hi:[1,0]
	v_pk_mul_f32 v[36:37], v[44:45], v[48:49] op_sel_hi:[1,0]
	v_pk_mul_f32 v[38:39], v[46:47], v[48:49] op_sel_hi:[1,0]
	v_pk_fma_f32 v[32:33], v[70:71], v[32:33], v[24:25]
	v_pk_fma_f32 v[34:35], v[72:73], v[34:35], v[26:27]
	v_pk_fma_f32 v[36:37], v[68:69], v[36:37], v[28:29]
	v_pk_fma_f32 v[38:39], v[74:75], v[38:39], v[30:31]
	v_cvt_pk_bf16_f32 v32, v32, v33
	v_cvt_pk_bf16_f32 v33, v34, v35
	v_cvt_pk_bf16_f32 v34, v36, v37
	v_cvt_pk_bf16_f32 v35, v38, v39
	global_store_dwordx4 v[40:41], v[32:35], off offset:1024

; #define GAS __attribute__((address_space(1)))
; __device__ __forceinline__ unsigned pk2(float lo, float hi) { const f32x2_t v = {lo, hi}; return __builtin_bit_cast(unsigned, __builtin_convertvector(v, bf16x2_t)); }
; __device__ __forceinline__ float shx(float v, int o, int lane) { return __builtin_bit_cast(float, __builtin_amdgcn_ds_bpermute((lane ^ o) << 2, __builtin_bit_cast(int, v))); }
; __device__ __forceinline__ float wave_sum(float v, int lane) {
;     ...
;     for (int o = 1; o < 64; o <<= 1) v += shx(v, o, lane);
; __device__ __forceinline__ void phase_mf(const Params& p, Frame& F, int l, const bool dry) {
;     ...
;             ss += (x0.x * x0.x + x0.y * x0.y) + (x0.z * x0.z + x0.w * x0.w) + (x1.x * x1.x + x1.y * x1.y) + (x1.z * x1.z + x1.w * x1.w); }
;         if (nxt) { const float rstd = rsqrtf(wave_sum(ss, F.lane) * (1.0f / D) + EPS);
; #pragma unroll
;             for (int j = 0; j < 2; ++j) { const int c0 = 512 * j + 8 * F.lane; v4u o; float hv[8];
; #pragma unroll
;                 for (int i = 0; i < 8; ++i) hv[i] = acc[8 * j + i] * rstd * Anv[j][i >> 2][i & 3] + Bnv[j][i >> 2][i & 3];
;                 o.x = pk2(hv[0], hv[1]); o.y = pk2(hv[2], hv[3]); o.z = pk2(hv[4], hv[5]); o.w = pk2(hv[6], hv[7]); *(GAS v4u*)(H + (size_t)row * D + c0) = o; } }
.LBB0_1516:
	v_mul_f32_e32 v48, v37, v37
	v_mul_f32_e32 v49, v39, v39
	v_fmac_f32_e32 v48, v36, v36
	v_fmac_f32_e32 v49, v38, v38
	v_add_f32_e32 v48, v48, v49
	v_mul_f32_e32 v49, v41, v41
	v_fmac_f32_e32 v49, v40, v40
	v_add_f32_e32 v48, v48, v49
	v_mul_f32_e32 v49, v43, v43
	v_fmac_f32_e32 v49, v42, v42
	v_add_f32_e32 v84, v49, v48
	v_pk_mul_f32 v[48:49], v[34:35], v[34:35]
	v_pk_mul_f32 v[50:51], v[32:33], v[32:33]
	s_mov_b32 s5, 0x800000
	v_pk_mov_b32 v[52:53], v[50:51], v[48:49] op_sel:[1,0]
	v_mov_b32_e32 v51, v49
	v_pk_add_f32 v[48:49], v[52:53], v[50:51]
	v_pk_mul_f32 v[50:51], v[46:47], v[46:47]
	v_pk_mul_f32 v[52:53], v[44:45], v[44:45]
	v_mov_b32_e32 v54, v50
	v_mov_b32_e32 v55, v52
	v_mov_b32_e32 v52, v51
	v_pk_add_f32 v[50:51], v[54:55], v[52:53]
	v_add_f32_e32 v48, v48, v49
	v_add_f32_e32 v48, v48, v51
	v_add_f32_e32 v48, v50, v48
	v_add_f32_e32 v48, v84, v48
	s_nop 1
	v_mov_b32_dpp v49, v48 quad_perm:[1,0,3,2] row_mask:0xf bank_mask:0xf
	s_waitcnt lgkmcnt(0)
	v_add_f32_e32 v48, v48, v49
	s_nop 1
	v_mov_b32_dpp v49, v48 quad_perm:[2,3,0,1] row_mask:0xf bank_mask:0xf
	s_waitcnt lgkmcnt(0)
	v_add_f32_e32 v48, v48, v49
	s_nop 1
	v_mov_b32_dpp v49, v48 quad_perm:[3,2,1,0] row_mask:0xf bank_mask:0xf
	s_nop 1
	v_mov_b32_dpp v49, v49 row_half_mirror row_mask:0xf bank_mask:0xf
	s_waitcnt lgkmcnt(0)
	v_add_f32_e32 v48, v48, v49
	s_nop 1
	v_mov_b32_dpp v49, v48 row_ror:8 row_mask:0xf bank_mask:0xf
	s_waitcnt lgkmcnt(0)
	v_add_f32_e32 v48, v48, v49
	v_mov_b32_e32 v49, v48
	s_nop 1
	v_permlane16_swap_b32 v49, v48
	s_waitcnt lgkmcnt(0)
	v_add_f32_e32 v48, v48, v49
	v_mov_b32_e32 v49, v48
	s_nop 1
	v_permlane32_swap_b32 v49, v48
	s_waitcnt lgkmcnt(0)
	v_add_f32_e32 v48, v48, v49
	v_fmamk_f32 v48, v48, 0x3a800000, v240
	v_mul_f32_e32 v49, 0x4b800000, v48
	v_cmp_gt_f32_e32 vcc, s5, v48
	s_nop 1
	v_cndmask_b32_e32 v48, v48, v49, vcc
	v_rsq_f32_e32 v48, v48
	s_nop 0
	v_mul_f32_e32 v49, 0x45800000, v48
	v_cndmask_b32_e32 v48, v48, v49, vcc
	v_pk_mul_f32 v[36:37], v[36:37], v[48:49] op_sel_hi:[1,0]
	v_pk_mul_f32 v[38:39], v[38:39], v[48:49] op_sel_hi:[1,0]
	v_pk_mul_f32 v[40:41], v[40:41], v[48:49] op_sel_hi:[1,0]
	v_pk_mul_f32 v[42:43], v[42:43], v[48:49] op_sel_hi:[1,0]
	v_pk_fma_f32 v[36:37], v[62:63], v[36:37], v[8:9]
	v_pk_fma_f32 v[38:39], v[64:65], v[38:39], v[10:11]
	v_pk_fma_f32 v[40:41], v[60:61], v[40:41], v[12:13]
	v_pk_fma_f32 v[42:43], v[66:67], v[42:43], v[14:15]
	v_cvt_pk_bf16_f32 v36, v36, v37
	v_cvt_pk_bf16_f32 v37, v38, v39
	v_cvt_pk_bf16_f32 v38, v40, v41
	v_cvt_pk_bf16_f32 v39, v42, v43
	v_lshl_add_u64 v[40:41], v[80:81], 0, s[6:7]
	global_store_dwordx4 v[40:41], v[36:39], off
	v_pk_mul_f32 v[32:33], v[32:33], v[48:49] op_sel_hi:[1,0]
	v_pk_mul_f32 v[34:35], v[34:35], v[48:49] op_sel_hi:[1,0]
	v_pk_mul_f32 v[36:37], v[44:45], v[48:49] op_sel_hi:[1,0]
	v_pk_mul_f32 v[38:39], v[46:47], v[48:49] op_sel_hi:[1,0]
	v_pk_fma_f32 v[32:33], v[70:71], v[32:33], v[24:25]
	v_pk_fma_f32 v[34:35], v[72:73], v[34:35], v[26:27]
	v_pk_fma_f32 v[36:37], v[68:69], v[36:37], v[28:29]
	v_pk_fma_f32 v[38:39], v[74:75], v[38:39], v[30:31]
	v_cvt_pk_bf16_f32 v32, v32, v33
	v_cvt_pk_bf16_f32 v33, v34, v35
	v_cvt_pk_bf16_f32 v34, v36, v37
	v_cvt_pk_bf16_f32 v35, v38, v39
	global_store_dwordx4 v[40:41], v[32:35], off offset:1024
	s_branch .LBB0_1438
